# attention tile loop: waves 4..7 take each tile barrier before their 16-exp tail instead of after it (half-group phase offset so the two waves of a SIMD stop running MFMA and VALU segments in lockstep)
# speedup vs baseline: 1.0079x; 1.0079x over previous
.LBB0_422:
	s_lshl_b32 s0, s39, 10
	s_and_b32 s6, s0, 0x800000
	s_lshl_b32 s0, s43, 1
	s_and_b32 s66, s0, 0x300
	s_lshl_b32 s0, s64, 11
	s_lshl_b32 s1, s64, 4
	s_and_b32 s0, s0, 0x2000
	s_and_b32 s1, s1, 0xffffff80
	s_add_i32 s1, s0, s1
	v_or_b32_e32 v171, s1, v170
	v_or_b32_e32 v0, v171, v169
	v_ashrrev_i32_e32 v1, 31, v0
	s_lshl_b32 s1, s64, 7
	v_lshlrev_b64 v[0:1], 10, v[0:1]
	s_and_b32 s65, s1, 0x180
	v_lshl_add_u64 v[0:1], s[86:87], 0, v[0:1]
	s_lshl_b32 s4, s65, 1
	s_mov_b32 s5, s7
	v_lshl_add_u64 v[0:1], v[0:1], 0, s[4:5]
	s_lshl_b32 s5, s0, 10
	s_add_u32 s0, s33, s5
	s_addc_u32 s1, s34, 0
	s_add_u32 s0, s0, s4
	v_mov_b32_e32 v174, v168
	v_lshl_add_u64 v[0:1], v[160:161], 1, v[0:1]
	s_addc_u32 s1, s1, 0
	v_lshl_add_u64 v[0:1], v[0:1], 0, v[162:163]
	v_ashrrev_i32_e32 v16, 4, v174
	s_add_u32 s5, s35, s5
	v_lshlrev_b32_e32 v20, 3, v174
	v_add_u32_e32 v18, 32, v16
	s_addc_u32 s16, s38, 0
	global_load_dwordx4 v[124:127], v[0:1], off
	global_load_dwordx4 v[120:123], v[0:1], off offset:32
	global_load_dwordx4 v[116:119], v[0:1], off offset:64
	global_load_dwordx4 v[112:115], v[0:1], off offset:96
	v_and_b32_e32 v0, 0x78, v20
	v_ashrrev_i32_e32 v17, 31, v16
	v_ashrrev_i32_e32 v19, 31, v18
	s_add_u32 s4, s5, s4
	v_lshlrev_b32_e32 v21, 1, v0
	v_lshlrev_b64 v[48:49], 10, v[16:17]
	v_lshlrev_b64 v[12:13], 10, v[18:19]
	s_addc_u32 s5, s16, 0
	v_or_b32_e32 v50, v48, v21
	v_mov_b32_e32 v51, v49
	v_or_b32_e32 v12, v12, v21
	v_lshl_add_u64 v[0:1], s[4:5], 0, v[50:51]
	v_lshl_add_u64 v[4:5], s[4:5], 0, v[12:13]
	s_barrier
	global_load_dwordx4 v[0:3], v[0:1], off
	s_nop 0
	global_load_dwordx4 v[4:7], v[4:5], off
	v_lshl_add_u64 v[8:9], s[0:1], 0, v[50:51]
	global_load_dwordx4 v[8:11], v[8:9], off
	v_lshl_add_u64 v[12:13], s[0:1], 0, v[12:13]
	global_load_dwordx4 v[12:15], v[12:13], off
	v_and_b32_e32 v22, 0xfffff0, v16
	v_lshlrev_b32_e32 v23, 1, v16
	v_lshrrev_b32_e32 v24, 1, v16
	v_and_b32_e32 v25, 3, v16
	v_and_or_b32 v22, v23, 8, v22
	v_and_or_b32 v23, v24, 4, v25
	v_and_b32_e32 v24, 0xfffff0, v18
	v_lshlrev_b32_e32 v25, 1, v18
	v_and_b32_e32 v17, 0x70, v174
	v_bfe_u32 v20, v20, 5, 2
	v_lshlrev_b32_e32 v16, 8, v16
	v_lshrrev_b32_e32 v22, 1, v22
	v_and_or_b32 v24, v25, 8, v24
	v_bitop3_b32 v183, v21, v16, v17 bitop3:0xde
	v_or_b32_e32 v16, v22, v20
	v_lshrrev_b32_e32 v22, 1, v24
	v_lshlrev_b32_e32 v23, 6, v23
	v_and_b32_e32 v26, 48, v21
	v_lshlrev_b32_e32 v16, 9, v16
	v_or_b32_e32 v20, v22, v20
	v_or3_b32 v184, v16, v23, v26
	v_lshlrev_b32_e32 v16, 9, v20
	v_bfe_u32 v172, v174, 5, 1
	v_ashrrev_i32_e32 v175, 8, v174
	v_lshlrev_b32_e32 v52, 4, v174
	v_or3_b32 v186, v16, v23, v26
	v_add_u32_e32 v84, 16, v184
	v_and_b32_e32 v173, 31, v174
	v_lshlrev_b32_e32 v19, 7, v175
	v_add_u32_e32 v24, 16, v183
	v_add_u32_e32 v85, 16, v186
	s_waitcnt vmcnt(0)
	v_lshlrev_b32_e32 v176, 4, v172
	v_lshlrev_b32_e32 v190, 8, v173
	v_and_b32_e32 v86, 63, v174
	v_lshl_add_u64 v[60:61], v[50:51], 0, s[14:15]
	v_lshl_add_u64 v[64:65], v[50:51], 0, s[36:37]
	v_lshl_add_u64 v[56:57], s[4:5], 0, v[64:65]
	v_lshl_add_u64 v[64:65], s[0:1], 0, v[64:65]
	s_cmp_lg_u32 16, -1
	s_cselect_b32 s16, 16, 0
	s_mov_b32 s17, s7
	s_mov_b32 s18, s7
	s_mov_b32 s19, s7
	s_mov_b32 s20, s7
	s_waitcnt vmcnt(3)
	ds_write_b128 v84, v[0:3]
	s_waitcnt vmcnt(2)
	ds_write_b128 v85, v[4:7]
	s_waitcnt vmcnt(1)
	ds_write_b128 v24, v[8:11] offset:49152
	v_and_b32_e32 v8, 0x70, v52
	v_lshlrev_b32_e32 v0, 8, v18
	v_bitop3_b32 v182, v176, v8, v19 bitop3:0x36
	v_bitop3_b32 v188, v21, v0, v17 bitop3:0xde
	v_add_u32_e32 v185, v182, v190
	v_add_u32_e32 v0, 16, v188
	v_add_u32_e32 v4, 16, v185
	s_waitcnt vmcnt(0)
	ds_write_b128 v0, v[12:15] offset:49152
	s_waitcnt lgkmcnt(0)
	s_barrier
	ds_read_b128 v[0:3], v4 offset:49152
	ds_read_b128 v[4:7], v4 offset:57344
	v_or_b32_e32 v9, v176, v19
	v_bitop3_b32 v187, v9, v8, 32 bitop3:0x36
	v_add_u32_e32 v189, v187, v190
	s_waitcnt lgkmcnt(0)
	v_mfma_f32_32x32x16_bf16 v[16:31], v[4:7], v[124:127], 0
	v_add_u32_e32 v4, 16, v189
	v_bitop3_b32 v193, v9, v8, s3 bitop3:0x36
	v_bitop3_b32 v191, v9, v8, 64 bitop3:0x36
	v_add_u32_e32 v194, v193, v190
	v_add_u32_e32 v192, v191, v190
	v_add_u32_e32 v8, 16, v194
	v_and_b32_e32 v5, 0x3fffffc0, v174
	v_mfma_f32_32x32x16_bf16 v[32:47], v[0:3], v[124:127], 0
	ds_read_b128 v[0:3], v4 offset:49152
	v_and_b32_e32 v11, 0xc0, v52
	v_add_u32_e32 v13, 16, v192
	ds_read_b128 v[52:55], v8 offset:57344
	v_lshl_add_u32 v177, v5, 2, s50
	ds_read_b128 v[4:7], v4 offset:57344
	v_lshlrev_b32_e32 v10, 3, v86
	s_waitcnt lgkmcnt(2)
	v_mfma_f32_32x32x16_bf16 v[32:47], v[0:3], v[120:123], v[32:47]
	v_lshlrev_b32_e32 v0, 1, v174
	v_and_b32_e32 v12, 32, v0
	ds_read_b128 v[0:3], v13 offset:49152
	v_and_or_b32 v11, v10, 24, v11
	s_mov_b32 s21, s7
	s_mov_b32 s22, s7
	s_mov_b32 s23, s7
	s_waitcnt lgkmcnt(0)
	v_mfma_f32_32x32x16_bf16 v[32:47], v[0:3], v[116:119], v[32:47]
	ds_read_b128 v[0:3], v8 offset:49152
	s_mov_b32 s24, s7
	s_mov_b32 s25, s7
	s_mov_b32 s26, s7
	s_mov_b32 s27, s7
	s_mov_b32 s28, s7
	s_mov_b32 s29, s7
	v_mfma_f32_32x32x16_bf16 v[16:31], v[4:7], v[120:123], v[16:31]
	v_and_b32_e32 v4, 0x100, v10
	v_or3_b32 v178, v11, v12, v4
	ds_read_b128 v[4:7], v13 offset:57344
	v_add_u32_e32 v181, s16, v178
	s_mov_b32 s16, s7
	s_mov_b32 s30, s7
	s_mov_b32 s31, s7
	s_waitcnt lgkmcnt(0)
	v_mfma_f32_32x32x16_bf16 v[16:31], v[4:7], v[116:119], v[16:31]
	v_lshl_add_u32 v179, v173, 2, v177
	v_mov_b32_e32 v196, 1.0
	v_mov_b32_e32 v180, 0
	v_mfma_f32_32x32x16_bf16 v[32:47], v[0:3], v[112:115], v[32:47]
	v_mov_b64_e32 v[0:1], s[16:17]
	v_mov_b64_e32 v[14:15], s[30:31]
	v_mov_b64_e32 v[2:3], s[18:19]
	v_mov_b64_e32 v[4:5], s[20:21]
	v_mov_b64_e32 v[6:7], s[22:23]
	v_mov_b64_e32 v[8:9], s[24:25]
	v_mov_b64_e32 v[10:11], s[26:27]
	v_mfma_f32_32x32x16_bf16 v[16:31], v[52:55], v[112:115], v[16:31]
	s_nop 3
	v_max_f32_e32 v52, v33, v33
	v_max_f32_e32 v53, v32, v32
	v_max_f32_e32 v52, v53, v52
	v_max3_f32 v52, v52, v34, v35
	v_max3_f32 v52, v52, v36, v37
	v_max3_f32 v52, v52, v38, v39
	v_max3_f32 v52, v52, v40, v41
	v_max3_f32 v52, v52, v42, v43
	v_max3_f32 v52, v52, v44, v45
	v_max3_f32 v66, v52, v46, v47
	v_lshl_add_u64 v[52:53], s[4:5], 0, v[60:61]
	v_lshl_add_u64 v[60:61], s[0:1], 0, v[60:61]
	global_load_dwordx4 v[52:55], v[52:53], off
	s_nop 0
	global_load_dwordx4 v[56:59], v[56:57], off
	v_mov_b64_e32 v[12:13], s[28:29]
	global_load_dwordx4 v[60:63], v[60:61], off
	s_mov_b32 s19, 1
	global_load_dwordx4 v[80:83], v[64:65], off
	v_max3_f32 v64, v66, v16, v17
	v_max3_f32 v64, v64, v18, v19
	v_max3_f32 v64, v64, v20, v21
	v_max3_f32 v64, v64, v22, v23
	v_max3_f32 v64, v64, v24, v25
	v_max3_f32 v64, v64, v26, v27
	v_max3_f32 v64, v64, v28, v29
	v_max3_f32 v70, v64, v30, v31
	v_lshl_add_u64 v[64:65], v[50:51], 0, s[40:41]
	v_lshl_add_u64 v[66:67], s[0:1], 0, v[64:65]
	v_lshl_add_u64 v[50:51], v[50:51], 0, s[44:45]
	v_lshl_add_u64 v[64:65], s[4:5], 0, v[64:65]
	v_lshl_add_u64 v[68:69], s[0:1], 0, v[50:51]
	global_load_dwordx4 v[136:139], v[66:67], off
	global_load_dwordx4 v[128:131], v[68:69], off
	v_lshl_add_u64 v[50:51], s[4:5], 0, v[50:51]
	global_load_dwordx4 v[140:143], v[64:65], off
	global_load_dwordx4 v[132:135], v[50:51], off
	v_mov_b32_e32 v71, v70
	s_nop 1
	v_permlane32_swap_b32_e32 v70, v71
	v_max_f32_e32 v50, v71, v71
	v_max_f32_e32 v51, v70, v70
	v_max_f32_e32 v50, v51, v50
	v_sub_f32_e32 v64, v16, v50
	v_add_u32_e32 v16, s58, v183
	v_sub_f32_e32 v32, v32, v50
	v_sub_f32_e32 v33, v33, v50
	v_sub_f32_e32 v34, v34, v50
	v_sub_f32_e32 v35, v35, v50
	v_sub_f32_e32 v36, v36, v50
	v_sub_f32_e32 v37, v37, v50
	v_sub_f32_e32 v38, v38, v50
	v_sub_f32_e32 v39, v39, v50
	v_sub_f32_e32 v40, v40, v50
	v_sub_f32_e32 v41, v41, v50
	v_sub_f32_e32 v42, v42, v50
	v_sub_f32_e32 v43, v43, v50
	v_sub_f32_e32 v44, v44, v50
	v_sub_f32_e32 v45, v45, v50
	v_sub_f32_e32 v46, v46, v50
	v_sub_f32_e32 v47, v47, v50
	v_sub_f32_e32 v66, v18, v50
	s_waitcnt vmcnt(4)
	s_waitcnt vmcnt(7)
	ds_write_b128 v84, v[52:55] offset:16384
	s_waitcnt vmcnt(6)
	ds_write_b128 v85, v[56:59] offset:16384
	v_and_b32_e32 v18, 15, v174
	s_waitcnt vmcnt(5)
	ds_write_b128 v16, v[60:63]
	v_add_u32_e32 v16, s58, v188
	v_sub_f32_e32 v65, v17, v50
	v_exp_f32_e32 v152, v32
	v_exp_f32_e32 v153, v33
	v_exp_f32_e32 v154, v34
	v_exp_f32_e32 v155, v35
	v_exp_f32_e32 v156, v36
	v_exp_f32_e32 v157, v37
	v_exp_f32_e32 v158, v38
	v_exp_f32_e32 v159, v39
	v_exp_f32_e32 v144, v40
	v_exp_f32_e32 v145, v41
	v_exp_f32_e32 v146, v42
	v_exp_f32_e32 v147, v43
	v_exp_f32_e32 v148, v44
	v_exp_f32_e32 v149, v45
	v_exp_f32_e32 v150, v46
	v_exp_f32_e32 v151, v47
	s_waitcnt vmcnt(4)
	ds_write_b128 v16, v[80:83]
	v_lshl_add_u64 v[16:17], s[6:7], 0, v[48:49]
	v_lshlrev_b32_e32 v18, 4, v18
	v_or3_b32 v16, v16, s66, v18
	v_add_f32_e32 v195, 0, v50
	v_sub_f32_e32 v79, v31, v50
	v_sub_f32_e32 v78, v30, v50
	v_sub_f32_e32 v77, v29, v50
	v_sub_f32_e32 v76, v28, v50
	v_sub_f32_e32 v75, v27, v50
	v_sub_f32_e32 v74, v26, v50
	v_sub_f32_e32 v73, v25, v50
	v_sub_f32_e32 v72, v24, v50
	v_sub_f32_e32 v71, v23, v50
	v_sub_f32_e32 v70, v22, v50
	v_sub_f32_e32 v69, v21, v50
	v_sub_f32_e32 v68, v20, v50
	v_sub_f32_e32 v67, v19, v50
	v_lshl_add_u64 v[166:167], s[12:13], 0, v[16:17]
	v_mov_b64_e32 v[62:63], v[14:15]
	v_mov_b64_e32 v[46:47], v[14:15]
	v_mov_b64_e32 v[30:31], v[14:15]
	v_cmp_gt_u32_e64 s[0:1], 32, v86
	v_mov_b64_e32 v[60:61], v[12:13]
	v_mov_b64_e32 v[58:59], v[10:11]
	v_mov_b64_e32 v[56:57], v[8:9]
	v_mov_b64_e32 v[54:55], v[6:7]
	v_mov_b64_e32 v[52:53], v[4:5]
	v_mov_b64_e32 v[50:51], v[2:3]
	v_mov_b64_e32 v[48:49], v[0:1]
	v_mov_b64_e32 v[44:45], v[12:13]
	v_mov_b64_e32 v[42:43], v[10:11]
	v_mov_b64_e32 v[40:41], v[8:9]
	v_mov_b64_e32 v[38:39], v[6:7]
	v_mov_b64_e32 v[36:37], v[4:5]
	v_mov_b64_e32 v[34:35], v[2:3]
	v_mov_b64_e32 v[32:33], v[0:1]
	v_mov_b64_e32 v[28:29], v[12:13]
	v_mov_b64_e32 v[26:27], v[10:11]
	v_mov_b64_e32 v[24:25], v[8:9]
	v_mov_b64_e32 v[22:23], v[6:7]
	v_mov_b64_e32 v[20:21], v[4:5]
	v_mov_b64_e32 v[18:19], v[2:3]
	v_mov_b64_e32 v[16:17], v[0:1]
	s_mov_b32 s6, 1
	s_mov_b32 s18, 0
	s_waitcnt lgkmcnt(0)
	s_barrier
	v_add_co_u32_e32 v242, vcc, s61, v166
	s_nop 1
	v_addc_co_u32_e32 v243, vcc, -1, v167, vcc
	s_nop 0
	v_readfirstlane_b32 s98, v242
	v_readfirstlane_b32 s99, v243
	s_nop 1
	v_subrev_u32_e32 v242, s98, v242
	v_add_u32_e32 v243, 0x8000, v242
	v_add_u32_e32 v244, 0x1000000, v242
	v_add_u32_e32 v245, 0x1008000, v242
	v_readfirstlane_b32 s100, v214
	s_lshr_b32 s100, s100, 8

.LBB0_425:
	ds_read_b64_tr_b16 v[202:203], v199 offset:0x600
	ds_read_b64_tr_b16 v[204:205], v199 offset:0xe00
	ds_read_b64_tr_b16 v[206:207], v199 offset:0x1600
	ds_read_b64_tr_b16 v[208:209], v199 offset:0x1e00
	ds_read_b64_tr_b16 v[210:211], v199 offset:0x2600
	ds_read_b64_tr_b16 v[212:213], v199 offset:0x2e00
	ds_read_b64_tr_b16 v[222:223], v199 offset:0x3600
	ds_read_b64_tr_b16 v[224:225], v199 offset:0x3e00
	s_add_i32 s4, s19, 1
	s_cmp_lg_u32 s19, 2
	s_cselect_b32 s18, s4, 0
	s_waitcnt lgkmcnt(6)
	v_mfma_f32_32x32x16_bf16 v[16:31], v[64:67], v[202:205], v[16:31]
	s_lshl_b32 s4, s18, 14
	s_add_i32 s17, s4, 16
	v_add_u32_e32 v64, s17, v184
	s_waitcnt vmcnt(4)
	s_waitcnt vmcnt(4)
	ds_write_b128 v64, v[132:135]
	v_add_u32_e32 v64, s17, v186
	ds_write_b128 v64, v[140:143]
	s_waitcnt lgkmcnt(6)
	v_mfma_f32_32x32x16_bf16 v[16:31], v[72:75], v[206:209], v[16:31]
	v_add_u32_e32 v64, s17, v183
	ds_write_b128 v64, v[128:131] offset:49152
	v_add_u32_e32 v64, s17, v188
	v_cmp_gt_f32_e32 vcc, 1.0, v200
	ds_write_b128 v64, v[136:139] offset:49152
	s_waitcnt lgkmcnt(6)
	v_mfma_f32_32x32x16_bf16 v[16:31], v[68:71], v[210:213], v[16:31]
	s_waitcnt lgkmcnt(4)
	v_mfma_f32_32x32x16_bf16 v[16:31], v[76:79], v[222:225], v[16:31]
	s_cmp_eq_u32 s100, 0
	s_cbranch_scc1 .Lpp_a0_e0
	s_waitcnt lgkmcnt(0)
	s_barrier
.Lpp_a0_e0:
	s_cbranch_vccz .LBB0_429
	s_and_saveexec_b64 s[4:5], s[0:1]
	ds_write_b32 v179, v200 offset:128
	s_or_b64 exec, exec, s[4:5]
	s_waitcnt lgkmcnt(0)
	v_add_u32_e32 v76, v177, v176
	ds_read_b128 v[64:67], v76 offset:224
	ds_read_b128 v[68:71], v76 offset:192
	ds_read_b128 v[72:75], v76 offset:160
	ds_read_b128 v[76:79], v76 offset:128
	s_waitcnt lgkmcnt(3)
	v_pk_mul_f32 v[12:13], v[12:13], v[64:65]
	s_waitcnt lgkmcnt(2)
	v_pk_mul_f32 v[8:9], v[8:9], v[68:69]
	s_waitcnt lgkmcnt(1)
	v_pk_mul_f32 v[4:5], v[4:5], v[72:73]
	v_pk_mul_f32 v[14:15], v[14:15], v[66:67]
	v_pk_mul_f32 v[10:11], v[10:11], v[70:71]
	v_pk_mul_f32 v[6:7], v[6:7], v[74:75]
	s_waitcnt lgkmcnt(0)
	v_pk_mul_f32 v[2:3], v[2:3], v[78:79]
	v_pk_mul_f32 v[0:1], v[0:1], v[76:77]
	v_pk_mul_f32 v[60:61], v[60:61], v[64:65]
	v_pk_mul_f32 v[56:57], v[56:57], v[68:69]
	v_pk_mul_f32 v[52:53], v[52:53], v[72:73]
	v_pk_mul_f32 v[62:63], v[62:63], v[66:67]
	v_pk_mul_f32 v[58:59], v[58:59], v[70:71]
	v_pk_mul_f32 v[54:55], v[54:55], v[74:75]
	v_pk_mul_f32 v[50:51], v[50:51], v[78:79]
	v_pk_mul_f32 v[48:49], v[48:49], v[76:77]
	v_pk_mul_f32 v[44:45], v[44:45], v[64:65]
	v_pk_mul_f32 v[40:41], v[40:41], v[68:69]
	v_pk_mul_f32 v[36:37], v[36:37], v[72:73]
	v_pk_mul_f32 v[46:47], v[46:47], v[66:67]
	v_pk_mul_f32 v[42:43], v[42:43], v[70:71]
	v_pk_mul_f32 v[38:39], v[38:39], v[74:75]
	v_pk_mul_f32 v[34:35], v[34:35], v[78:79]
	v_pk_mul_f32 v[32:33], v[32:33], v[76:77]
	v_pk_mul_f32 v[28:29], v[28:29], v[64:65]
	v_pk_mul_f32 v[24:25], v[24:25], v[68:69]
	v_pk_mul_f32 v[20:21], v[20:21], v[72:73]
	v_pk_mul_f32 v[30:31], v[30:31], v[66:67]
	v_pk_mul_f32 v[26:27], v[26:27], v[70:71]
	v_pk_mul_f32 v[22:23], v[22:23], v[74:75]
	v_pk_mul_f32 v[18:19], v[18:19], v[78:79]
	v_pk_mul_f32 v[16:17], v[16:17], v[76:77]
.LBB0_429:
	v_exp_f32_e32 v199, v96
	v_exp_f32_e32 v221, v97
	v_exp_f32_e32 v226, v98
	v_exp_f32_e32 v227, v99
	v_exp_f32_e32 v228, v100
	v_exp_f32_e32 v229, v101
	v_exp_f32_e32 v230, v102
	v_exp_f32_e32 v231, v103
	v_exp_f32_e32 v232, v104
	v_exp_f32_e32 v233, v105
	v_exp_f32_e32 v234, v106
	v_exp_f32_e32 v235, v107
	v_exp_f32_e32 v236, v108
	v_exp_f32_e32 v237, v109
	v_exp_f32_e32 v238, v110
	v_exp_f32_e32 v239, v111
	s_waitcnt lgkmcnt(0)
	s_cmp_lg_u32 s100, 0
	s_cbranch_scc1 .Lpp_a0_l0
	s_barrier
.Lpp_a0_l0:
	v_add_u32_e32 v96, s17, v185
	ds_read_b128 v[202:205], v96 offset:49152
	ds_read_b128 v[206:209], v96 offset:57344
	v_xor_b32_e32 v64, 0x80000000, v195
	v_mov_b32_e32 v65, v64
	v_mov_b64_e32 v[66:67], v[64:65]
	v_mov_b64_e32 v[68:69], v[64:65]
	v_mov_b64_e32 v[70:71], v[64:65]
	v_mov_b64_e32 v[72:73], v[64:65]
	v_mov_b64_e32 v[74:75], v[64:65]
	v_mov_b64_e32 v[76:77], v[64:65]
	v_mov_b64_e32 v[78:79], v[64:65]
	v_add_u32_e32 v201, s17, v189
	v_exp_f32_e32 v80, v80
	s_waitcnt lgkmcnt(1)
	v_mfma_f32_32x32x16_bf16 v[96:111], v[202:205], v[124:127], v[64:79]
	v_exp_f32_e32 v81, v81
	v_exp_f32_e32 v82, v82
	v_exp_f32_e32 v83, v83
	v_exp_f32_e32 v84, v84
	v_exp_f32_e32 v85, v85
	v_exp_f32_e32 v86, v86
	v_exp_f32_e32 v87, v87
	s_waitcnt lgkmcnt(0)
	v_mfma_f32_32x32x16_bf16 v[64:79], v[206:209], v[124:127], v[64:79]
	ds_read_b128 v[202:205], v201 offset:49152
	ds_read_b128 v[206:209], v201 offset:57344
	v_add_u32_e32 v201, s17, v192
	v_exp_f32_e32 v240, v91
	v_exp_f32_e32 v241, v92
	v_cvt_pk_bf16_f32 v91, v230, v231
	v_cvt_pk_bf16_f32 v92, v232, v233
	s_waitcnt lgkmcnt(1)
	v_mfma_f32_32x32x16_bf16 v[96:111], v[202:205], v[120:123], v[96:111]
	ds_read_b128 v[202:205], v201 offset:49152
	ds_read_b128 v[210:213], v201 offset:57344
	v_add_u32_e32 v201, s17, v194
	s_waitcnt lgkmcnt(1)
	v_mfma_f32_32x32x16_bf16 v[96:111], v[202:205], v[116:119], v[96:111]
	v_exp_f32_e32 v203, v88
	v_add_f32_e32 v88, 0, v199
	v_add_f32_e32 v88, v221, v88
	v_add_f32_e32 v88, v226, v88
	v_add_f32_e32 v88, v227, v88
	v_add_f32_e32 v88, v228, v88
	v_add_f32_e32 v88, v229, v88
	v_add_f32_e32 v88, v230, v88
	v_add_f32_e32 v88, v231, v88
	v_add_f32_e32 v88, v232, v88
	v_add_f32_e32 v88, v233, v88
	v_mfma_f32_32x32x16_bf16 v[64:79], v[206:209], v[120:123], v[64:79]
	v_add_f32_e32 v88, v234, v88
	v_add_f32_e32 v88, v235, v88
	v_add_f32_e32 v88, v236, v88
	v_add_f32_e32 v88, v237, v88
	v_add_f32_e32 v88, v238, v88
	v_add_f32_e32 v88, v239, v88
	v_add_f32_e32 v88, v80, v88
	v_add_f32_e32 v88, v81, v88
	s_waitcnt lgkmcnt(0)
	v_mfma_f32_32x32x16_bf16 v[64:79], v[210:213], v[116:119], v[64:79]
	v_add_f32_e32 v88, v82, v88
	v_add_f32_e32 v88, v83, v88
	v_add_f32_e32 v88, v84, v88
	ds_read_b128 v[206:209], v201 offset:49152
	ds_read_b128 v[222:225], v201 offset:57344
	v_exp_f32_e32 v204, v89
	v_add_f32_e32 v88, v85, v88
	v_exp_f32_e32 v205, v90
	v_add_f32_e32 v88, v86, v88
	v_add_f32_e32 v88, v87, v88
	v_add_f32_e32 v88, v203, v88
	v_exp_f32_e32 v210, v93
	v_add_f32_e32 v88, v204, v88
	v_exp_f32_e32 v211, v94
	s_waitcnt lgkmcnt(1)
	v_mfma_f32_32x32x16_bf16 v[96:111], v[206:209], v[112:115], v[96:111]
	v_add_f32_e32 v88, v205, v88
	v_exp_f32_e32 v212, v95
	v_add_f32_e32 v88, v240, v88
	v_add_f32_e32 v88, v241, v88
	v_add_f32_e32 v88, v210, v88
	v_add_f32_e32 v88, v211, v88
	v_add_f32_e32 v201, v212, v88
	s_waitcnt lgkmcnt(0)
	v_mfma_f32_32x32x16_bf16 v[64:79], v[222:225], v[112:115], v[64:79]
	v_mov_b32_e32 v202, v201
	v_cvt_pk_bf16_f32 v88, v199, v221
	v_cvt_pk_bf16_f32 v89, v226, v227
	v_cvt_pk_bf16_f32 v90, v228, v229
	v_cvt_pk_bf16_f32 v93, v234, v235
	v_cvt_pk_bf16_f32 v94, v236, v237
	v_cvt_pk_bf16_f32 v95, v238, v239
	v_cvt_pk_bf16_f32 v80, v80, v81
	v_cvt_pk_bf16_f32 v81, v82, v83
	v_cvt_pk_bf16_f32 v82, v84, v85
	v_cvt_pk_bf16_f32 v83, v86, v87
	v_cvt_pk_bf16_f32 v84, v203, v204
	v_cvt_pk_bf16_f32 v85, v205, v240
	v_cvt_pk_bf16_f32 v86, v241, v210
	v_cvt_pk_bf16_f32 v87, v211, v212
	v_permlane32_swap_b32_e32 v201, v202
	v_permlane32_swap_b32_e32 v88, v90
	v_permlane32_swap_b32_e32 v89, v91
	v_permlane32_swap_b32_e32 v92, v94
	v_permlane32_swap_b32_e32 v93, v95
	v_permlane32_swap_b32_e32 v80, v82
	v_permlane32_swap_b32_e32 v81, v83
	v_permlane32_swap_b32_e32 v84, v86
	v_permlane32_swap_b32_e32 v85, v87
	s_cmpk_gt_u32 s6, 0x7c
	s_cselect_b64 s[4:5], -1, 0
	s_and_b64 vcc, exec, s[4:5]
	s_cbranch_vccnz .Lattn_a0_lastw
	global_load_dwordx4 v[132:135], v244, s[98:99]
	global_load_dwordx4 v[128:131], v242, s[98:99]
	global_load_dwordx4 v[140:143], v245, s[98:99]
	global_load_dwordx4 v[136:139], v243, s[98:99]
	s_add_u32 s98, s98, 0x10000
	s_addc_u32 s99, s99, 0

.LBB0_432:
	ds_read_b64_tr_b16 v[204:205], v203 offset:0x600
	ds_read_b64_tr_b16 v[206:207], v203 offset:0xe00
	ds_read_b64_tr_b16 v[208:209], v203 offset:0x1600
	ds_read_b64_tr_b16 v[210:211], v203 offset:0x1e00
	ds_read_b64_tr_b16 v[222:223], v203 offset:0x2600
	ds_read_b64_tr_b16 v[224:225], v203 offset:0x2e00
	ds_read_b64_tr_b16 v[226:227], v203 offset:0x3600
	ds_read_b64_tr_b16 v[228:229], v203 offset:0x3e00
	s_add_i32 s16, s18, 1
	s_cmp_lg_u32 s18, 2
	s_cselect_b32 s19, s16, 0
	s_waitcnt lgkmcnt(6)
	v_mfma_f32_32x32x16_bf16 v[16:31], v[88:91], v[204:207], v[16:31]
	s_lshl_b32 s16, s19, 14
	s_add_i32 s16, s16, 16
	s_waitcnt vmcnt(4)
	v_add_u32_e32 v88, s16, v184
	ds_write_b128 v88, v[144:147]
	v_cmp_gt_f32_e32 vcc, 1.0, v199
	s_waitcnt lgkmcnt(5)
	v_mfma_f32_32x32x16_bf16 v[16:31], v[92:95], v[208:211], v[16:31]
	s_waitcnt lgkmcnt(3)
	v_mfma_f32_32x32x16_bf16 v[16:31], v[80:83], v[222:225], v[16:31]
	v_add_u32_e32 v80, s16, v186
	ds_write_b128 v80, v[148:151]
	v_add_u32_e32 v80, s16, v183
	ds_write_b128 v80, v[152:155] offset:49152
	v_add_u32_e32 v80, s16, v188
	ds_write_b128 v80, v[156:159] offset:49152
	s_waitcnt lgkmcnt(4)
	v_mfma_f32_32x32x16_bf16 v[16:31], v[84:87], v[226:229], v[16:31]
	s_cmp_eq_u32 s100, 0
	s_cbranch_scc1 .Lpp_a0_e1
	s_waitcnt lgkmcnt(0)
	s_barrier
.Lpp_a0_e1:
	s_cbranch_vccz .LBB0_436
	s_and_saveexec_b64 s[16:17], s[0:1]
	ds_write_b32 v179, v199 offset:128
	s_or_b64 exec, exec, s[16:17]
	s_waitcnt lgkmcnt(0)
	v_add_u32_e32 v92, v177, v176
	ds_read_b128 v[80:83], v92 offset:224
	ds_read_b128 v[84:87], v92 offset:192
	ds_read_b128 v[88:91], v92 offset:160
	ds_read_b128 v[92:95], v92 offset:128
	s_waitcnt lgkmcnt(3)
	v_pk_mul_f32 v[12:13], v[12:13], v[80:81]
	s_waitcnt lgkmcnt(2)
	v_pk_mul_f32 v[8:9], v[8:9], v[84:85]
	s_waitcnt lgkmcnt(1)
	v_pk_mul_f32 v[4:5], v[4:5], v[88:89]
	v_pk_mul_f32 v[14:15], v[14:15], v[82:83]
	v_pk_mul_f32 v[10:11], v[10:11], v[86:87]
	v_pk_mul_f32 v[6:7], v[6:7], v[90:91]
	s_waitcnt lgkmcnt(0)
	v_pk_mul_f32 v[2:3], v[2:3], v[94:95]
	v_pk_mul_f32 v[0:1], v[0:1], v[92:93]
	v_pk_mul_f32 v[60:61], v[60:61], v[80:81]
	v_pk_mul_f32 v[56:57], v[56:57], v[84:85]
	v_pk_mul_f32 v[52:53], v[52:53], v[88:89]
	v_pk_mul_f32 v[62:63], v[62:63], v[82:83]
	v_pk_mul_f32 v[58:59], v[58:59], v[86:87]
	v_pk_mul_f32 v[54:55], v[54:55], v[90:91]
	v_pk_mul_f32 v[50:51], v[50:51], v[94:95]
	v_pk_mul_f32 v[48:49], v[48:49], v[92:93]
	v_pk_mul_f32 v[44:45], v[44:45], v[80:81]
	v_pk_mul_f32 v[40:41], v[40:41], v[84:85]
	v_pk_mul_f32 v[36:37], v[36:37], v[88:89]
	v_pk_mul_f32 v[46:47], v[46:47], v[82:83]
	v_pk_mul_f32 v[42:43], v[42:43], v[86:87]
	v_pk_mul_f32 v[38:39], v[38:39], v[90:91]
	v_pk_mul_f32 v[34:35], v[34:35], v[94:95]
	v_pk_mul_f32 v[32:33], v[32:33], v[92:93]
	v_pk_mul_f32 v[28:29], v[28:29], v[80:81]
	v_pk_mul_f32 v[24:25], v[24:25], v[84:85]
	v_pk_mul_f32 v[20:21], v[20:21], v[88:89]
	v_pk_mul_f32 v[30:31], v[30:31], v[82:83]
	v_pk_mul_f32 v[26:27], v[26:27], v[86:87]
	v_pk_mul_f32 v[22:23], v[22:23], v[90:91]
	v_pk_mul_f32 v[18:19], v[18:19], v[94:95]
	v_pk_mul_f32 v[16:17], v[16:17], v[92:93]
.LBB0_436:
	v_exp_f32_e32 v152, v96
	v_exp_f32_e32 v153, v97
	v_exp_f32_e32 v154, v98
	v_exp_f32_e32 v155, v99
	v_exp_f32_e32 v156, v100
	v_exp_f32_e32 v157, v101
	v_exp_f32_e32 v158, v102
	v_exp_f32_e32 v159, v103
	v_exp_f32_e32 v144, v104
	v_exp_f32_e32 v145, v105
	v_exp_f32_e32 v146, v106
	v_exp_f32_e32 v147, v107
	v_exp_f32_e32 v148, v108
	v_exp_f32_e32 v149, v109
	v_exp_f32_e32 v150, v110
	v_exp_f32_e32 v151, v111
	v_add_f32_e32 v80, v197, v198
	v_fmac_f32_e32 v80, v196, v180
	v_add_f32_e32 v180, v201, v202
	v_fmac_f32_e32 v180, v80, v200
	s_add_i32 s6, s6, 2
	s_and_b64 vcc, exec, s[4:5]
	s_waitcnt lgkmcnt(0)
	s_cmp_lg_u32 s100, 0
	s_cbranch_scc1 .Lpp_a0_l1
	s_barrier
.Lpp_a0_l1:
	s_cbranch_vccnz .LBB0_440
	v_mov_b32_e32 v196, v199
	s_branch .LBB0_423

.LBB0_805:
	s_lshl_b32 s0, s39, 10
	s_and_b32 s6, s0, 0x800000
	s_lshl_b32 s0, s43, 1
	s_and_b32 s65, s0, 0x300
	s_lshl_b32 s0, s2, 11
	s_lshl_b32 s1, s2, 4
	s_and_b32 s0, s0, 0x2000
	s_and_b32 s1, s1, 0xffffff80
	s_add_i32 s1, s0, s1
	v_or_b32_e32 v171, s1, v170
	v_or_b32_e32 v0, v171, v169
	v_ashrrev_i32_e32 v1, 31, v0
	s_lshl_b32 s1, s2, 7
	v_lshlrev_b64 v[0:1], 10, v[0:1]
	s_and_b32 s64, s1, 0x180
	v_lshl_add_u64 v[0:1], s[86:87], 0, v[0:1]
	s_lshl_b32 s4, s64, 1
	s_mov_b32 s5, s7
	v_lshl_add_u64 v[0:1], v[0:1], 0, s[4:5]
	s_lshl_b32 s5, s0, 10
	s_add_u32 s0, s33, s5
	s_addc_u32 s1, s34, 0
	s_add_u32 s0, s0, s4
	v_mov_b32_e32 v174, v168
	v_lshl_add_u64 v[0:1], v[160:161], 1, v[0:1]
	s_addc_u32 s1, s1, 0
	v_lshl_add_u64 v[0:1], v[0:1], 0, v[162:163]
	v_ashrrev_i32_e32 v16, 4, v174
	s_add_u32 s5, s35, s5
	v_lshlrev_b32_e32 v20, 3, v174
	v_add_u32_e32 v18, 32, v16
	s_addc_u32 s16, s38, 0
	global_load_dwordx4 v[124:127], v[0:1], off
	global_load_dwordx4 v[120:123], v[0:1], off offset:32
	global_load_dwordx4 v[116:119], v[0:1], off offset:64
	global_load_dwordx4 v[112:115], v[0:1], off offset:96
	v_and_b32_e32 v0, 0x78, v20
	v_ashrrev_i32_e32 v17, 31, v16
	v_ashrrev_i32_e32 v19, 31, v18
	s_add_u32 s4, s5, s4
	v_lshlrev_b32_e32 v21, 1, v0
	v_lshlrev_b64 v[48:49], 10, v[16:17]
	v_lshlrev_b64 v[12:13], 10, v[18:19]
	s_addc_u32 s5, s16, 0
	v_or_b32_e32 v50, v48, v21
	v_mov_b32_e32 v51, v49
	v_or_b32_e32 v12, v12, v21
	v_lshl_add_u64 v[0:1], s[4:5], 0, v[50:51]
	v_lshl_add_u64 v[4:5], s[4:5], 0, v[12:13]
	s_barrier
	global_load_dwordx4 v[0:3], v[0:1], off
	s_nop 0
	global_load_dwordx4 v[4:7], v[4:5], off
	v_lshl_add_u64 v[8:9], s[0:1], 0, v[50:51]
	global_load_dwordx4 v[8:11], v[8:9], off
	v_lshl_add_u64 v[12:13], s[0:1], 0, v[12:13]
	global_load_dwordx4 v[12:15], v[12:13], off
	v_and_b32_e32 v22, 0xfffff0, v16
	v_lshlrev_b32_e32 v23, 1, v16
	v_lshrrev_b32_e32 v24, 1, v16
	v_and_b32_e32 v25, 3, v16
	v_and_or_b32 v22, v23, 8, v22
	v_and_or_b32 v23, v24, 4, v25
	v_and_b32_e32 v24, 0xfffff0, v18
	v_lshlrev_b32_e32 v25, 1, v18
	v_and_b32_e32 v17, 0x70, v174
	v_bfe_u32 v20, v20, 5, 2
	v_lshlrev_b32_e32 v16, 8, v16
	v_lshrrev_b32_e32 v22, 1, v22
	v_and_or_b32 v24, v25, 8, v24
	v_bitop3_b32 v183, v21, v16, v17 bitop3:0xde
	v_or_b32_e32 v16, v22, v20
	v_lshrrev_b32_e32 v22, 1, v24
	v_lshlrev_b32_e32 v23, 6, v23
	v_and_b32_e32 v26, 48, v21
	v_lshlrev_b32_e32 v16, 9, v16
	v_or_b32_e32 v20, v22, v20
	v_or3_b32 v184, v16, v23, v26
	v_lshlrev_b32_e32 v16, 9, v20
	v_bfe_u32 v172, v174, 5, 1
	v_ashrrev_i32_e32 v175, 8, v174
	v_lshlrev_b32_e32 v52, 4, v174
	v_or3_b32 v186, v16, v23, v26
	v_add_u32_e32 v84, 16, v184
	v_and_b32_e32 v173, 31, v174
	v_lshlrev_b32_e32 v19, 7, v175
	v_add_u32_e32 v24, 16, v183
	v_add_u32_e32 v85, 16, v186
	s_waitcnt vmcnt(0)
	v_lshlrev_b32_e32 v176, 4, v172
	v_lshlrev_b32_e32 v190, 8, v173
	v_and_b32_e32 v86, 63, v174
	v_lshl_add_u64 v[60:61], v[50:51], 0, s[14:15]
	v_lshl_add_u64 v[64:65], v[50:51], 0, s[36:37]
	v_lshl_add_u64 v[56:57], s[4:5], 0, v[64:65]
	v_lshl_add_u64 v[64:65], s[0:1], 0, v[64:65]
	s_cmp_lg_u32 16, -1
	s_cselect_b32 s16, 16, 0
	s_mov_b32 s17, s7
	s_mov_b32 s18, s7
	s_mov_b32 s19, s7
	s_mov_b32 s20, s7
	s_waitcnt vmcnt(3)
	ds_write_b128 v84, v[0:3]
	s_waitcnt vmcnt(2)
	ds_write_b128 v85, v[4:7]
	s_waitcnt vmcnt(1)
	ds_write_b128 v24, v[8:11] offset:49152
	v_and_b32_e32 v8, 0x70, v52
	v_lshlrev_b32_e32 v0, 8, v18
	v_bitop3_b32 v182, v176, v8, v19 bitop3:0x36
	v_bitop3_b32 v188, v21, v0, v17 bitop3:0xde
	v_add_u32_e32 v185, v182, v190
	v_add_u32_e32 v0, 16, v188
	v_add_u32_e32 v4, 16, v185
	s_waitcnt vmcnt(0)
	ds_write_b128 v0, v[12:15] offset:49152
	s_waitcnt lgkmcnt(0)
	s_barrier
	ds_read_b128 v[0:3], v4 offset:49152
	ds_read_b128 v[4:7], v4 offset:57344
	v_or_b32_e32 v9, v176, v19
	v_bitop3_b32 v187, v9, v8, 32 bitop3:0x36
	v_add_u32_e32 v189, v187, v190
	s_waitcnt lgkmcnt(0)
	v_mfma_f32_32x32x16_bf16 v[16:31], v[4:7], v[124:127], 0
	v_add_u32_e32 v4, 16, v189
	v_bitop3_b32 v193, v9, v8, s3 bitop3:0x36
	v_bitop3_b32 v191, v9, v8, 64 bitop3:0x36
	v_add_u32_e32 v194, v193, v190
	v_add_u32_e32 v192, v191, v190
	v_add_u32_e32 v8, 16, v194
	v_and_b32_e32 v5, 0x3fffffc0, v174
	v_mfma_f32_32x32x16_bf16 v[32:47], v[0:3], v[124:127], 0
	ds_read_b128 v[0:3], v4 offset:49152
	v_and_b32_e32 v11, 0xc0, v52
	v_add_u32_e32 v13, 16, v192
	ds_read_b128 v[52:55], v8 offset:57344
	v_lshl_add_u32 v177, v5, 2, s50
	ds_read_b128 v[4:7], v4 offset:57344
	v_lshlrev_b32_e32 v10, 3, v86
	s_waitcnt lgkmcnt(2)
	v_mfma_f32_32x32x16_bf16 v[32:47], v[0:3], v[120:123], v[32:47]
	v_lshlrev_b32_e32 v0, 1, v174
	v_and_b32_e32 v12, 32, v0
	ds_read_b128 v[0:3], v13 offset:49152
	v_and_or_b32 v11, v10, 24, v11
	s_mov_b32 s21, s7
	s_mov_b32 s22, s7
	s_mov_b32 s23, s7
	s_waitcnt lgkmcnt(0)
	v_mfma_f32_32x32x16_bf16 v[32:47], v[0:3], v[116:119], v[32:47]
	ds_read_b128 v[0:3], v8 offset:49152
	s_mov_b32 s24, s7
	s_mov_b32 s25, s7
	s_mov_b32 s26, s7
	s_mov_b32 s27, s7
	s_mov_b32 s28, s7
	s_mov_b32 s29, s7
	v_mfma_f32_32x32x16_bf16 v[16:31], v[4:7], v[120:123], v[16:31]
	v_and_b32_e32 v4, 0x100, v10
	v_or3_b32 v178, v11, v12, v4
	ds_read_b128 v[4:7], v13 offset:57344
	v_add_u32_e32 v181, s16, v178
	s_mov_b32 s16, s7
	s_mov_b32 s30, s7
	s_mov_b32 s31, s7
	s_waitcnt lgkmcnt(0)
	v_mfma_f32_32x32x16_bf16 v[16:31], v[4:7], v[116:119], v[16:31]
	v_lshl_add_u32 v179, v173, 2, v177
	v_mov_b32_e32 v196, 1.0
	v_mov_b32_e32 v180, 0
	v_mfma_f32_32x32x16_bf16 v[32:47], v[0:3], v[112:115], v[32:47]
	v_mov_b64_e32 v[0:1], s[16:17]
	v_mov_b64_e32 v[14:15], s[30:31]
	v_mov_b64_e32 v[2:3], s[18:19]
	v_mov_b64_e32 v[4:5], s[20:21]
	v_mov_b64_e32 v[6:7], s[22:23]
	v_mov_b64_e32 v[8:9], s[24:25]
	v_mov_b64_e32 v[10:11], s[26:27]
	v_mfma_f32_32x32x16_bf16 v[16:31], v[52:55], v[112:115], v[16:31]
	s_nop 3
	v_max_f32_e32 v52, v33, v33
	v_max_f32_e32 v53, v32, v32
	v_max_f32_e32 v52, v53, v52
	v_max3_f32 v52, v52, v34, v35
	v_max3_f32 v52, v52, v36, v37
	v_max3_f32 v52, v52, v38, v39
	v_max3_f32 v52, v52, v40, v41
	v_max3_f32 v52, v52, v42, v43
	v_max3_f32 v52, v52, v44, v45
	v_max3_f32 v66, v52, v46, v47
	v_lshl_add_u64 v[52:53], s[4:5], 0, v[60:61]
	v_lshl_add_u64 v[60:61], s[0:1], 0, v[60:61]
	global_load_dwordx4 v[52:55], v[52:53], off
	s_nop 0
	global_load_dwordx4 v[56:59], v[56:57], off
	v_mov_b64_e32 v[12:13], s[28:29]
	global_load_dwordx4 v[60:63], v[60:61], off
	s_mov_b32 s19, 1
	global_load_dwordx4 v[80:83], v[64:65], off
	v_max3_f32 v64, v66, v16, v17
	v_max3_f32 v64, v64, v18, v19
	v_max3_f32 v64, v64, v20, v21
	v_max3_f32 v64, v64, v22, v23
	v_max3_f32 v64, v64, v24, v25
	v_max3_f32 v64, v64, v26, v27
	v_max3_f32 v64, v64, v28, v29
	v_max3_f32 v70, v64, v30, v31
	v_lshl_add_u64 v[64:65], v[50:51], 0, s[40:41]
	v_lshl_add_u64 v[66:67], s[0:1], 0, v[64:65]
	v_lshl_add_u64 v[50:51], v[50:51], 0, s[44:45]
	v_lshl_add_u64 v[64:65], s[4:5], 0, v[64:65]
	v_lshl_add_u64 v[68:69], s[0:1], 0, v[50:51]
	global_load_dwordx4 v[136:139], v[66:67], off
	global_load_dwordx4 v[128:131], v[68:69], off
	v_lshl_add_u64 v[50:51], s[4:5], 0, v[50:51]
	global_load_dwordx4 v[140:143], v[64:65], off
	global_load_dwordx4 v[132:135], v[50:51], off
	v_mov_b32_e32 v71, v70
	s_nop 1
	v_permlane32_swap_b32_e32 v70, v71
	v_max_f32_e32 v50, v71, v71
	v_max_f32_e32 v51, v70, v70
	v_max_f32_e32 v50, v51, v50
	v_sub_f32_e32 v64, v16, v50
	v_add_u32_e32 v16, s58, v183
	v_sub_f32_e32 v32, v32, v50
	v_sub_f32_e32 v33, v33, v50
	v_sub_f32_e32 v34, v34, v50
	v_sub_f32_e32 v35, v35, v50
	v_sub_f32_e32 v36, v36, v50
	v_sub_f32_e32 v37, v37, v50
	v_sub_f32_e32 v38, v38, v50
	v_sub_f32_e32 v39, v39, v50
	v_sub_f32_e32 v40, v40, v50
	v_sub_f32_e32 v41, v41, v50
	v_sub_f32_e32 v42, v42, v50
	v_sub_f32_e32 v43, v43, v50
	v_sub_f32_e32 v44, v44, v50
	v_sub_f32_e32 v45, v45, v50
	v_sub_f32_e32 v46, v46, v50
	v_sub_f32_e32 v47, v47, v50
	v_sub_f32_e32 v66, v18, v50
	s_waitcnt vmcnt(4)
	s_waitcnt vmcnt(7)
	ds_write_b128 v84, v[52:55] offset:16384
	s_waitcnt vmcnt(6)
	ds_write_b128 v85, v[56:59] offset:16384
	v_and_b32_e32 v18, 15, v174
	s_waitcnt vmcnt(5)
	ds_write_b128 v16, v[60:63]
	v_add_u32_e32 v16, s58, v188
	v_sub_f32_e32 v65, v17, v50
	v_exp_f32_e32 v152, v32
	v_exp_f32_e32 v153, v33
	v_exp_f32_e32 v154, v34
	v_exp_f32_e32 v155, v35
	v_exp_f32_e32 v156, v36
	v_exp_f32_e32 v157, v37
	v_exp_f32_e32 v158, v38
	v_exp_f32_e32 v159, v39
	v_exp_f32_e32 v144, v40
	v_exp_f32_e32 v145, v41
	v_exp_f32_e32 v146, v42
	v_exp_f32_e32 v147, v43
	v_exp_f32_e32 v148, v44
	v_exp_f32_e32 v149, v45
	v_exp_f32_e32 v150, v46
	v_exp_f32_e32 v151, v47
	s_waitcnt vmcnt(4)
	ds_write_b128 v16, v[80:83]
	v_lshl_add_u64 v[16:17], s[6:7], 0, v[48:49]
	v_lshlrev_b32_e32 v18, 4, v18
	v_or3_b32 v16, v16, s65, v18
	v_add_f32_e32 v195, 0, v50
	v_sub_f32_e32 v79, v31, v50
	v_sub_f32_e32 v78, v30, v50
	v_sub_f32_e32 v77, v29, v50
	v_sub_f32_e32 v76, v28, v50
	v_sub_f32_e32 v75, v27, v50
	v_sub_f32_e32 v74, v26, v50
	v_sub_f32_e32 v73, v25, v50
	v_sub_f32_e32 v72, v24, v50
	v_sub_f32_e32 v71, v23, v50
	v_sub_f32_e32 v70, v22, v50
	v_sub_f32_e32 v69, v21, v50
	v_sub_f32_e32 v68, v20, v50
	v_sub_f32_e32 v67, v19, v50
	v_lshl_add_u64 v[166:167], s[12:13], 0, v[16:17]
	v_mov_b64_e32 v[62:63], v[14:15]
	v_mov_b64_e32 v[46:47], v[14:15]
	v_mov_b64_e32 v[30:31], v[14:15]
	v_cmp_gt_u32_e64 s[0:1], 32, v86
	v_mov_b64_e32 v[60:61], v[12:13]
	v_mov_b64_e32 v[58:59], v[10:11]
	v_mov_b64_e32 v[56:57], v[8:9]
	v_mov_b64_e32 v[54:55], v[6:7]
	v_mov_b64_e32 v[52:53], v[4:5]
	v_mov_b64_e32 v[50:51], v[2:3]
	v_mov_b64_e32 v[48:49], v[0:1]
	v_mov_b64_e32 v[44:45], v[12:13]
	v_mov_b64_e32 v[42:43], v[10:11]
	v_mov_b64_e32 v[40:41], v[8:9]
	v_mov_b64_e32 v[38:39], v[6:7]
	v_mov_b64_e32 v[36:37], v[4:5]
	v_mov_b64_e32 v[34:35], v[2:3]
	v_mov_b64_e32 v[32:33], v[0:1]
	v_mov_b64_e32 v[28:29], v[12:13]
	v_mov_b64_e32 v[26:27], v[10:11]
	v_mov_b64_e32 v[24:25], v[8:9]
	v_mov_b64_e32 v[22:23], v[6:7]
	v_mov_b64_e32 v[20:21], v[4:5]
	v_mov_b64_e32 v[18:19], v[2:3]
	v_mov_b64_e32 v[16:17], v[0:1]
	s_mov_b32 s6, 1
	s_mov_b32 s18, 0
	s_waitcnt lgkmcnt(0)
	s_barrier
	v_add_co_u32_e32 v242, vcc, s61, v166
	s_nop 1
	v_addc_co_u32_e32 v243, vcc, -1, v167, vcc
	s_nop 0
	v_readfirstlane_b32 s98, v242
	v_readfirstlane_b32 s99, v243
	s_nop 1
	v_subrev_u32_e32 v242, s98, v242
	v_add_u32_e32 v243, 0x8000, v242
	v_add_u32_e32 v244, 0x1000000, v242
	v_add_u32_e32 v245, 0x1008000, v242
	v_readfirstlane_b32 s100, v214
	s_lshr_b32 s100, s100, 8
